# code placement: one 4-byte pad ahead of the layer loop (same instructions as the previous version)
# speedup vs baseline: 1.0084x; 1.0038x over previous
.LBB0_103:
	s_load_dwordx16 s[48:63], s[0:1], 0x40
	v_writelane_b32 v250, s44, 32
	s_xor_b64 s[0:1], s[4:5], -1
	s_cmp_eq_u32 s20, 0
	v_writelane_b32 v250, s45, 33
	s_waitcnt lgkmcnt(0)
	v_writelane_b32 v250, s48, 34
	v_readfirstlane_b32 s27, v0
	s_mul_i32 s2, s30, s23
	v_writelane_b32 v250, s49, 35
	v_writelane_b32 v250, s50, 36
	v_writelane_b32 v250, s51, 37
	v_writelane_b32 v250, s52, 38
	v_writelane_b32 v250, s53, 39
	v_writelane_b32 v250, s54, 40
	v_writelane_b32 v250, s55, 41
	v_writelane_b32 v250, s56, 42
	v_writelane_b32 v250, s57, 43
	v_writelane_b32 v250, s58, 44
	v_writelane_b32 v250, s59, 45
	v_writelane_b32 v250, s60, 46
	v_writelane_b32 v250, s61, 47
	v_writelane_b32 v250, s62, 48
	v_writelane_b32 v250, s63, 49
	v_writelane_b32 v250, s0, 50
	s_mul_i32 s2, s2, s22
	v_mov_b32_e32 v194, 0x358637bd
	v_writelane_b32 v250, s1, 51
	s_cselect_b64 s[0:1], -1, 0
	s_cmp_eq_u32 s21, 24
	s_cselect_b64 s[6:7], -1, 0
	s_and_b64 s[0:1], s[0:1], s[6:7]
	s_cmpk_eq_i32 s22, 0x100
	s_cselect_b64 s[6:7], -1, 0
	s_and_b64 s[0:1], s[0:1], s[6:7]
	s_add_u32 s6, s42, 0x6c00000
	v_writelane_b32 v250, s0, 52
	s_addc_u32 s7, s43, 0
	v_mov_b32_e32 v145, 0
	v_writelane_b32 v250, s1, 53
	s_add_u32 s0, s42, 0x100000
	s_addc_u32 s1, s43, 0
	s_add_u32 s66, s42, 0x8c00000
	s_addc_u32 s67, s43, 0
	v_writelane_b32 v250, s0, 54
	s_add_u32 s24, s42, 0x8c01000
	s_addc_u32 s25, s43, 0
	v_writelane_b32 v250, s1, 55
	s_lshl_b32 s0, s27, 6
	v_writelane_b32 v250, s0, 56
	s_lshl_b32 s0, s27, 8
	s_and_b32 s0, s0, 0x3f00
	s_add_u32 s0, s42, s0
	s_addc_u32 s1, s43, 0
	s_add_u32 s8, s0, 0x8000
	s_addc_u32 s9, s1, 0
	s_and_b64 s[0:1], s[4:5], exec
	s_cselect_b32 s1, s9, 0
	v_writelane_b32 v250, s8, 57
	s_cselect_b32 s0, s8, 0
	v_mov_b32_e32 v195, 1
	v_writelane_b32 v250, s9, 58
	v_writelane_b32 v250, s0, 59
	v_mov_b32_e32 v196, 0x260
	v_mov_b64_e32 v[148:149], 0x57f
	v_writelane_b32 v250, s1, 60
	s_add_u32 s0, s42, 0xe00000
	v_writelane_b32 v250, s0, 61
	s_addc_u32 s0, s43, 0
	s_cmpk_lt_i32 s27, 0x580
	v_writelane_b32 v250, s0, 62
	s_cselect_b64 s[0:1], -1, 0
	v_writelane_b32 v250, s0, 63
	s_ashr_i32 s23, s27, 31
	s_ashr_i32 s26, s22, 31
	v_writelane_b32 v251, s1, 0
	s_lshr_b32 s0, s23, 29
	s_add_i32 s1, s27, s0
	s_ashr_i32 s0, s1, 3
	s_and_b32 s1, s1, -8
	s_sub_i32 s1, s27, s1
	s_cmpk_gt_i32 s27, 0x7f
	s_cselect_b64 s[4:5], -1, 0
	v_writelane_b32 v251, s4, 1
	s_add_i32 s8, s46, 0xfffffc00
	v_readlane_b32 s48, v250, 16
	v_writelane_b32 v251, s5, 2
	s_lshl_b32 s4, s27, 3
	s_add_i32 s4, s31, s4
	s_add_i32 s5, s4, 0xfffffc00
	v_writelane_b32 v251, s8, 3
	s_cmpk_lt_i32 s5, 0x840
	v_writelane_b32 v251, s5, 4
	s_cselect_b64 s[8:9], -1, 0
	v_writelane_b32 v251, s8, 5
	s_add_i32 s5, s34, 0
	v_readlane_b32 s60, v250, 28
	v_writelane_b32 v251, s9, 6
	s_add_u32 s8, s42, 0x5b80000
	v_writelane_b32 v251, s5, 7
	s_addc_u32 s9, s43, 0
	v_writelane_b32 v251, s8, 8
	v_readlane_b32 s61, v250, 29
	v_readlane_b32 s62, v250, 30
	v_writelane_b32 v251, s9, 9
	s_add_u32 s8, s60, 0x1000
	s_addc_u32 s9, s61, 0
	v_writelane_b32 v251, s8, 10
	v_readlane_b32 s63, v250, 31
	v_readlane_b32 s56, v250, 24
	v_writelane_b32 v251, s9, 11
	s_add_u32 s8, s62, 0x1600000
	s_addc_u32 s9, s63, 0
	v_writelane_b32 v251, s8, 12
	s_cmp_lg_u64 s[60:61], 0
	s_mov_b64 s[60:61], s[6:7]
	v_writelane_b32 v251, s9, 13
	s_cselect_b64 s[6:7], -1, 0
	v_writelane_b32 v251, s6, 14
	v_readlane_b32 s57, v250, 25
	v_readlane_b32 s49, v250, 17
	v_writelane_b32 v251, s7, 15
	s_add_u32 s6, s42, 0x6680000
	s_addc_u32 s7, s43, 0
	v_writelane_b32 v251, s6, 16
	v_readlane_b32 s54, v250, 22
	v_readlane_b32 s55, v250, 23
	v_writelane_b32 v251, s7, 17
	s_add_u32 s6, s36, 0xb00000
	s_addc_u32 s7, s37, 0
	s_lshl_b32 s5, s22, 1
	s_add_i32 s5, s27, s5
	v_writelane_b32 v251, s6, 18
	s_add_i32 s28, s5, 0xffffff80
	v_readlane_b32 s50, v250, 18
	v_writelane_b32 v251, s7, 19
	s_add_u32 s6, s42, 0x200000
	v_writelane_b32 v251, s6, 20
	s_addc_u32 s6, s43, 0
	v_writelane_b32 v251, s6, 21
	s_add_u32 s6, s42, 0x2680000
	v_writelane_b32 v251, s6, 22
	s_addc_u32 s6, s43, 0
	v_writelane_b32 v251, s6, 23
	s_add_u32 s6, s42, 0x600000
	s_addc_u32 s7, s43, 0
	v_writelane_b32 v251, s6, 24
	s_cmpk_gt_i32 s27, 0x9f
	v_readlane_b32 s51, v250, 19
	v_writelane_b32 v251, s7, 25
	s_cselect_b64 s[6:7], -1, 0
	v_writelane_b32 v251, s6, 26
	v_readlane_b32 s58, v250, 26
	v_readlane_b32 s59, v250, 27
	v_writelane_b32 v251, s7, 27
	s_add_i32 s6, s4, 0xfffffb00
	s_mov_b32 s4, s46
	v_writelane_b32 v251, s4, 28
	v_readlane_b32 s53, v250, 21
	s_mov_b32 s53, s23
	v_writelane_b32 v251, s5, 29
	s_add_i32 s4, s46, 0xfffffb00
	s_cmpk_lt_i32 s6, 0xa80
	v_writelane_b32 v251, s4, 30
	s_cselect_b64 s[8:9], -1, 0
	v_writelane_b32 v251, s8, 31
	v_mov_b64_e32 v[150:151], 0x100
	v_mov_b64_e32 v[152:153], 0xff
	v_writelane_b32 v251, s9, 32
	s_add_u32 s8, s42, 0x2280000
	s_addc_u32 s9, s43, 0
	v_writelane_b32 v251, s8, 33
	s_movk_i32 s23, 0xf000
	s_mov_b64 s[62:63], 0x40000
	v_writelane_b32 v251, s9, 34
	s_add_u32 s8, s42, 0x2480000
	s_addc_u32 s9, s43, 0
	v_writelane_b32 v251, s8, 35
	s_mov_b64 s[70:71], 0x80
	s_mov_b64 s[96:97], 0x100
	v_writelane_b32 v251, s9, 36
	s_add_u32 s8, s42, 0x2a80000
	s_addc_u32 s9, s43, 0
	v_writelane_b32 v251, s8, 37
	s_mov_b64 s[34:35], 0xc0100
	s_mov_b64 s[72:73], 0xb0180
	v_writelane_b32 v251, s9, 38
	s_add_u32 s8, s42, 0x2c80000
	s_addc_u32 s9, s43, 0
	v_writelane_b32 v251, s8, 39
	s_mov_b64 s[74:75], 0x40100
	s_mov_b64 s[76:77], 0x48000
	v_writelane_b32 v251, s9, 40
	s_add_u32 s8, s42, 0x5580000
	s_addc_u32 s9, s43, 0
	v_writelane_b32 v251, s8, 41
	s_mov_b64 s[78:79], 0x50000
	s_mov_b64 s[80:81], 0x58000
	v_writelane_b32 v251, s9, 42
	s_add_u32 s8, s56, 0x800000
	s_addc_u32 s9, s57, 0
	v_writelane_b32 v251, s8, 43
	s_mov_b64 s[56:57], 0xb0100
	s_mov_b64 s[82:83], 0x40180
	v_writelane_b32 v251, s9, 44
	s_add_u32 s8, s42, 0x200
	s_addc_u32 s9, s43, 0
	v_writelane_b32 v251, s8, 45
	s_mov_b64 s[86:87], 0x4000
	v_readlane_b32 s52, v250, 20
	v_writelane_b32 v251, s9, 46
	s_add_u32 s8, s42, 0x1000
	s_addc_u32 s9, s43, 0
	v_writelane_b32 v251, s8, 47
	s_nop 1
	v_writelane_b32 v251, s9, 48
	s_add_u32 s8, s42, 0x1100
	s_addc_u32 s9, s43, 0
	v_writelane_b32 v251, s8, 49
	s_nop 1
	v_writelane_b32 v251, s9, 50
	s_add_u32 s8, s42, 0x1200
	s_addc_u32 s9, s43, 0
	v_writelane_b32 v251, s8, 51
	s_nop 1
	v_writelane_b32 v251, s9, 52
	s_add_u32 s8, s42, 0x1300
	s_addc_u32 s9, s43, 0
	v_writelane_b32 v251, s8, 53
	s_cmp_eq_u32 s3, 15
	s_nop 0
	v_writelane_b32 v251, s9, 54
	s_cselect_b64 s[8:9], -1, 0
	v_writelane_b32 v251, s8, 55
	s_cmp_eq_u32 s3, 14
	s_nop 0
	v_writelane_b32 v251, s9, 56
	s_cselect_b64 s[8:9], -1, 0
	v_writelane_b32 v251, s8, 57
	s_cmp_eq_u32 s3, 13
	s_nop 0
	v_writelane_b32 v251, s9, 58
	s_cselect_b64 s[8:9], -1, 0
	v_writelane_b32 v251, s8, 59
	s_cmp_eq_u32 s3, 12
	s_nop 0
	v_writelane_b32 v251, s9, 60
	s_cselect_b64 s[8:9], -1, 0
	v_writelane_b32 v251, s8, 61
	s_cmp_eq_u32 s3, 11
	s_nop 0
	v_writelane_b32 v251, s9, 62
	s_cselect_b64 s[8:9], -1, 0
	v_writelane_b32 v251, s8, 63
	s_cmp_eq_u32 s3, 10
	s_nop 0
	v_writelane_b32 v252, s9, 0
	s_cselect_b64 s[8:9], -1, 0
	v_writelane_b32 v252, s8, 1
	s_cmp_eq_u32 s3, 9
	s_nop 0
	v_writelane_b32 v252, s9, 2
	s_cselect_b64 s[8:9], -1, 0
	v_writelane_b32 v252, s8, 3
	s_cmp_eq_u32 s3, 8
	s_nop 0
	v_writelane_b32 v252, s9, 4
	s_cselect_b64 s[8:9], -1, 0
	v_writelane_b32 v252, s8, 5
	s_cmp_eq_u32 s3, 7
	s_nop 0
	v_writelane_b32 v252, s9, 6
	s_cselect_b64 s[8:9], -1, 0
	v_writelane_b32 v252, s8, 7
	s_cmp_eq_u32 s3, 6
	s_nop 0
	v_writelane_b32 v252, s9, 8
	s_cselect_b64 s[8:9], -1, 0
	v_writelane_b32 v252, s8, 9
	s_cmp_eq_u32 s3, 5
	s_nop 0
	v_writelane_b32 v252, s9, 10
	s_cselect_b64 s[8:9], -1, 0
	v_writelane_b32 v252, s8, 11
	s_cmp_eq_u32 s3, 4
	s_nop 0
	v_writelane_b32 v252, s9, 12
	s_cselect_b64 s[8:9], -1, 0
	v_writelane_b32 v252, s8, 13
	s_cmp_eq_u32 s3, 3
	s_nop 0
	v_writelane_b32 v252, s9, 14
	s_cselect_b64 s[8:9], -1, 0
	v_writelane_b32 v252, s8, 15
	s_cmp_eq_u32 s3, 2
	s_nop 0
	v_writelane_b32 v252, s9, 16
	s_cselect_b64 s[8:9], -1, 0
	v_writelane_b32 v252, s8, 17
	s_cmp_eq_u32 s3, 1
	s_nop 0
	v_writelane_b32 v252, s9, 18
	s_cselect_b64 s[8:9], -1, 0
	v_writelane_b32 v252, s8, 19
	s_cmp_eq_u32 s3, 0
	s_nop 0
	v_writelane_b32 v252, s9, 20
	s_cselect_b64 s[8:9], -1, 0
	v_writelane_b32 v252, s8, 21
	s_cmpk_eq_i32 s2, 0x100
	s_nop 0
	v_writelane_b32 v252, s9, 22
	v_writelane_b32 v252, s2, 23
	s_cselect_b64 s[8:9], -1, 0
	s_lshl_b32 s2, s3, 8
	s_add_u32 s2, s42, s2
	v_writelane_b32 v252, s8, 24
	s_addc_u32 s3, s43, 0
	s_nop 0
	v_writelane_b32 v252, s9, 25
	s_add_u32 s8, s2, 0x1400
	s_addc_u32 s9, s3, 0
	v_writelane_b32 v252, s8, 26
	s_add_u32 s2, s2, 0x2400
	s_addc_u32 s3, s3, 0
	v_writelane_b32 v252, s9, 27
	v_writelane_b32 v252, s2, 28
	s_nop 1
	v_writelane_b32 v252, s3, 29
	s_add_u32 s2, s42, 0x3400
	s_addc_u32 s3, s43, 0
	v_writelane_b32 v252, s2, 30
	s_nop 1
	v_writelane_b32 v252, s3, 31
	s_add_u32 s2, s42, 0x3500
	s_addc_u32 s3, s43, 0
	v_writelane_b32 v252, s2, 32
	s_cmpk_lt_i32 s27, 0x100
	s_nop 0
	v_writelane_b32 v252, s3, 33
	s_cselect_b64 s[2:3], -1, 0
	v_writelane_b32 v252, s2, 34
	s_nop 1
	v_writelane_b32 v252, s3, 35
	s_lshl_b32 s2, s1, 5
	s_cmpk_lt_i32 s27, 0x200
	s_cselect_b64 s[8:9], -1, 0
	s_lshl_b32 s3, s1, 6
	v_writelane_b32 v252, s8, 36
	s_cmpk_lt_i32 s27, 0x300
	s_nop 0
	v_writelane_b32 v252, s9, 37
	s_cselect_b64 s[8:9], -1, 0
	s_add_i32 s4, s5, 0xffffff40
	s_add_u32 s29, s42, 0xec00000
	s_addc_u32 s30, s43, 0
	v_writelane_b32 v252, s8, 38
	s_add_u32 s31, s42, 0xf400000
	s_addc_u32 s33, s43, 0
	v_writelane_b32 v252, s9, 39
	v_writelane_b32 v252, s4, 40
	s_add_u32 s4, s42, 0x400000
	v_writelane_b32 v252, s4, 41
	s_addc_u32 s4, s43, 0
	v_writelane_b32 v252, s4, 42
	s_add_u32 s4, s42, 0xa00000
	s_addc_u32 s5, s43, 0
	v_writelane_b32 v252, s4, 43
	s_cmpk_lt_i32 s6, 0x1000
	s_nop 0
	v_writelane_b32 v252, s5, 44
	v_writelane_b32 v252, s6, 45
	s_cselect_b64 s[4:5], -1, 0
	v_writelane_b32 v252, s4, 46
	s_nop 1
	v_writelane_b32 v252, s5, 47
	s_add_u32 s4, s42, 0x3780000
	s_addc_u32 s5, s43, 0
	v_writelane_b32 v252, s4, 48
	s_nop 1
	v_writelane_b32 v252, s5, 49
	s_add_u32 s4, s42, 0x3d00000
	s_addc_u32 s5, s43, 0
	v_writelane_b32 v252, s4, 50
	s_nop 1
	v_writelane_b32 v252, s5, 51
	v_readlane_b32 s4, v250, 0
	v_readlane_b32 s5, v250, 1
	v_readlane_b32 s6, v250, 2
	v_readlane_b32 s7, v250, 3
	v_readlane_b32 s8, v250, 4
	v_readlane_b32 s9, v250, 5
	v_readlane_b32 s10, v250, 6
	v_readlane_b32 s11, v250, 7
	v_readlane_b32 s12, v250, 8
	v_readlane_b32 s13, v250, 9
	v_readlane_b32 s14, v250, 10
	v_readlane_b32 s15, v250, 11
	v_readlane_b32 s16, v250, 12
	v_readlane_b32 s17, v250, 13
	v_readlane_b32 s18, v250, 14
	v_readlane_b32 s19, v250, 15
	s_mov_b64 s[4:5], s[8:9]
	s_mov_b64 s[6:7], s[10:11]
	s_mov_b64 s[8:9], s[12:13]
	s_mov_b64 s[10:11], s[14:15]
	s_mov_b64 s[12:13], s[16:17]
	s_mov_b64 s[14:15], s[18:19]
	s_add_u32 s14, s4, 0x1000
	s_addc_u32 s15, s5, 0
	v_writelane_b32 v252, s14, 52
	s_add_u32 s6, s6, 0x1600000
	s_addc_u32 s7, s7, 0
	v_writelane_b32 v252, s15, 53
	v_writelane_b32 v252, s6, 54
	s_cmp_lg_u64 s[4:5], 0
	s_cselect_b64 s[4:5], -1, 0
	v_writelane_b32 v252, s7, 55
	v_writelane_b32 v252, s4, 56
	s_nop 1
	v_writelane_b32 v252, s5, 57
	s_add_u32 s4, s42, 0x4800000
	s_addc_u32 s5, s43, 0
	v_writelane_b32 v252, s4, 58
	s_nop 1
	v_writelane_b32 v252, s5, 59
	s_add_u32 s4, s8, 0xb00000
	s_addc_u32 s5, s9, 0
	v_writelane_b32 v252, s4, 60
	s_nop 1
	v_writelane_b32 v252, s5, 61
	s_add_u32 s4, s42, 0x4d80000
	s_addc_u32 s5, s43, 0
	v_writelane_b32 v252, s4, 62
	s_nop 1
	v_writelane_b32 v252, s5, 63
	s_add_u32 s4, s10, 0x1000
	s_addc_u32 s5, s11, 0
	v_writelane_b32 v253, s4, 0
	s_nop 1
	v_writelane_b32 v253, s5, 1
	s_add_u32 s4, s12, 0x800000
	s_addc_u32 s5, s13, 0
	v_writelane_b32 v253, s4, 2
	s_cmp_lg_u64 s[10:11], 0
	s_nop 0
	v_writelane_b32 v253, s5, 3
	s_cselect_b64 s[4:5], -1, 0
	v_writelane_b32 v253, s4, 4
	s_nop 1
	v_writelane_b32 v253, s5, 5
	s_add_u32 s4, s42, 0x5180000
	s_addc_u32 s5, s43, 0
	v_writelane_b32 v253, s4, 6
	s_nop 1
	v_writelane_b32 v253, s5, 7
	s_add_u32 s4, s48, 0x400000
	s_addc_u32 s5, s49, 0
	v_writelane_b32 v253, s4, 8
	s_nop 1
	v_writelane_b32 v253, s5, 9
	s_add_u32 s4, s54, 0x400000
	s_addc_u32 s5, s55, 0
	v_writelane_b32 v253, s4, 10
	s_movk_i32 s54, 0x1800
	s_mov_b32 s55, 0x58000
	v_writelane_b32 v253, s5, 11
	s_add_u32 s4, s42, 0x5380000
	s_addc_u32 s5, s43, 0
	v_writelane_b32 v253, s4, 12
	s_nop 1
	v_writelane_b32 v253, s5, 13
	s_add_u32 s4, s50, 0x1000
	s_addc_u32 s5, s51, 0
	v_writelane_b32 v253, s4, 14
	s_nop 1
	v_writelane_b32 v253, s5, 15
	s_add_u32 s4, s42, 0x5980000
	s_addc_u32 s5, s43, 0
	v_writelane_b32 v253, s4, 16
	s_nop 1
	v_writelane_b32 v253, s5, 17
	s_add_u32 s4, s58, 0x400000
	s_addc_u32 s5, s59, 0
	v_writelane_b32 v253, s4, 18
	s_cmp_gt_i32 s21, 11
	s_mov_b64 s[58:59], 0x180
	v_writelane_b32 v253, s5, 19
	s_cselect_b64 s[4:5], -1, 0
	v_writelane_b32 v253, s4, 20
	s_cmp_lt_i32 s20, 13
	s_nop 0
	v_writelane_b32 v253, s5, 21
	s_cselect_b64 s[4:5], -1, 0
	v_writelane_b32 v253, s4, 22
	s_cmp_gt_i32 s21, 12
	s_nop 0
	v_writelane_b32 v253, s5, 23
	s_cselect_b64 s[4:5], -1, 0
	v_writelane_b32 v253, s4, 24
	s_cmp_lt_i32 s1, 0
	s_nop 0
	v_writelane_b32 v253, s5, 25
	s_mul_i32 s4, s1, 33
	s_cselect_b32 s4, s4, s2
	s_movk_i32 s2, 0xb1
	s_cselect_b32 s2, s2, 0xb0
	s_mul_i32 s2, s1, s2
	s_mulk_i32 s1, 0x41
	s_cselect_b32 s1, s1, s3
	s_add_i32 s2, s2, s0
	s_mul_hi_i32 s3, s2, 0x2e8ba2e9
	s_lshr_b32 s5, s3, 31
	s_ashr_i32 s3, s3, 5
	s_add_i32 s3, s3, s5
	s_mul_i32 s5, s3, 0xb0
	s_sub_i32 s2, s2, s5
	s_bfe_u32 s5, s2, 0x3001c
	s_add_i32 s5, s2, s5
	s_and_b32 s6, s5, 0xfff8
	s_sub_i32 s2, s2, s6
	s_sext_i32_i16 s2, s2
	s_lshl_b32 s6, s3, 11
	s_lshl_b32 s7, s2, 8
	s_add_i32 s6, s6, s7
	s_sext_i32_i16 s5, s5
	s_lshl_b32 s3, s3, 3
	v_writelane_b32 v253, s6, 26
	s_add_i32 s6, s3, s2
	s_ashr_i32 s2, s5, 3
	v_writelane_b32 v253, s2, 27
	s_lshr_b32 s2, s5, 3
	s_bfe_i64 s[2:3], s[2:3], 0x100000
	s_lshl_b64 s[2:3], s[2:3], 19
	v_writelane_b32 v253, s2, 28
	s_ashr_i32 s7, s6, 31
	s_nop 0
	v_writelane_b32 v253, s3, 29
	s_mov_b32 s2, s6
	v_writelane_b32 v253, s2, 30
	s_nop 1
	v_writelane_b32 v253, s3, 31
	s_lshl_b64 s[2:3], s[6:7], 19
	s_add_u32 s2, s60, s2
	s_addc_u32 s3, s61, s3
	s_add_u32 s6, s2, 0x40000
	v_writelane_b32 v253, s2, 32
	s_addc_u32 s7, s3, 0
	s_nop 0
	v_writelane_b32 v253, s3, 33
	s_add_i32 s2, s4, s0
	s_ashr_i32 s3, s2, 31
	s_lshr_b32 s3, s3, 27
	s_add_i32 s3, s2, s3
	s_and_b32 s4, s3, 0xffe0
	s_sub_i32 s2, s2, s4
	s_bfe_i32 s4, s2, 0x80000
	s_bfe_u32 s4, s4, 0x3000c
	s_add_i32 s4, s2, s4
	s_and_b32 s5, s4, 0xf8
	v_writelane_b32 v253, s6, 34
	s_sub_i32 s2, s2, s5
	s_ashr_i32 s5, s3, 5
	v_writelane_b32 v253, s7, 35
	s_sext_i32_i8 s6, s2
	s_bfe_i32 s2, s4, 0x80000
	s_sext_i32_i16 s2, s2
	s_lshl_b32 s3, s5, 3
	s_add_i32 s12, s3, s6
	s_ashr_i32 s11, s2, 3
	s_lshr_b32 s2, s2, 3
	s_ashr_i32 s13, s12, 31
	s_bfe_i64 s[2:3], s[2:3], 0x100000
	s_mul_i32 s7, s12, 0x180000
	s_mul_hi_i32 s4, s12, 0x180000
	s_add_u32 s8, s66, s7
	s_addc_u32 s9, s67, s4
	s_add_u32 s14, s8, 0xc0000
	v_writelane_b32 v253, s8, 36
	s_addc_u32 s15, s9, 0
	s_add_i32 s0, s1, s0
	s_ashr_i32 s1, s0, 31
	s_lshr_b32 s1, s1, 26
	s_add_i32 s1, s0, s1
	v_writelane_b32 v253, s9, 37
	s_and_b32 s8, s1, 0xffc0
	s_sub_i32 s0, s0, s8
	s_bfe_i32 s8, s0, 0x80000
	s_bfe_u32 s8, s8, 0x3000c
	s_add_i32 s8, s0, s8
	s_and_b32 s9, s8, 0xf8
	s_sub_i32 s0, s0, s9
	s_ashr_i32 s1, s1, 6
	s_sext_i32_i8 s0, s0
	v_writelane_b32 v253, s14, 38
	s_lshl_b32 s9, s1, 11
	s_lshl_b32 s10, s0, 8
	s_bfe_i32 s8, s8, 0x80000
	v_writelane_b32 v253, s15, 39
	s_add_i32 s9, s9, s10
	s_lshl_b32 s1, s1, 3
	s_sext_i32_i16 s8, s8
	v_writelane_b32 v253, s9, 40
	s_add_i32 s14, s1, s0
	s_ashr_i32 s0, s8, 3
	v_writelane_b32 v253, s0, 41
	s_lshr_b32 s0, s8, 3
	s_bfe_i64 s[0:1], s[0:1], 0x100000
	s_lshl_b64 s[0:1], s[0:1], 19
	v_writelane_b32 v253, s0, 42
	s_ashr_i32 s15, s14, 31
	s_nop 0
	v_writelane_b32 v253, s1, 43
	s_mov_b32 s0, s14
	v_writelane_b32 v253, s0, 44
	s_nop 1
	v_writelane_b32 v253, s1, 45
	s_lshl_b64 s[0:1], s[14:15], 19
	s_add_u32 s0, s60, s0
	s_addc_u32 s1, s61, s1
	s_add_u32 s8, s0, 0x40000
	v_writelane_b32 v253, s0, 46
	s_addc_u32 s9, s1, 0
	s_nop 0
	v_writelane_b32 v253, s1, 47
	v_writelane_b32 v253, s8, 48
	s_nop 1
	v_writelane_b32 v253, s9, 49
	s_lshl_b64 s[8:9], s[2:3], 19
	s_add_u32 s0, s24, s7
	v_writelane_b32 v253, s24, 50
	s_addc_u32 s1, s25, s4
	s_add_u32 s2, s0, 0xc0000
	v_writelane_b32 v253, s25, 51
	v_writelane_b32 v253, s0, 52
	s_addc_u32 s3, s1, 0
	s_nop 0
	v_writelane_b32 v253, s1, 53
	v_writelane_b32 v253, s2, 54
	s_lshl_b32 s0, s5, 11
	s_lshl_b32 s1, s6, 8
	v_writelane_b32 v253, s3, 55
	s_add_i32 s0, s0, s1
	v_writelane_b32 v253, s0, 56
	s_ashr_i32 s0, s12, 4
	s_mov_b32 s2, s12
	s_ashr_i32 s1, s0, 31
	v_writelane_b32 v253, s2, 57
	s_lshl_b64 s[0:1], s[0:1], 21
	s_nop 0
	v_writelane_b32 v253, s3, 58
	s_lshl_b64 s[2:3], s[12:13], 19
	s_add_u32 s4, s31, s8
	s_addc_u32 s5, s33, s9
	s_add_u32 s4, s4, s0
	s_addc_u32 s5, s5, s1
	s_add_u32 s6, s4, 0x40000
	v_writelane_b32 v253, s31, 59
	s_addc_u32 s7, s5, 0
	v_writelane_b32 v253, s33, 60
	s_add_u32 s2, s60, s2
	v_writelane_b32 v253, s6, 61
	s_addc_u32 s3, s61, s3
	s_movk_i32 s33, 0xe000
	v_writelane_b32 v253, s7, 62
	s_add_u32 s6, s2, 0x40000
	v_writelane_b32 v253, s2, 63
	s_addc_u32 s7, s3, 0
	s_nop 0
	v_writelane_b32 v254, s3, 0
	v_writelane_b32 v254, s6, 1
	s_add_u32 s2, s4, 0x40080
	s_nop 0
	v_writelane_b32 v254, s7, 2
	v_writelane_b32 v254, s4, 3
	s_addc_u32 s3, s5, 0
	s_add_u32 s0, s29, s0
	v_writelane_b32 v254, s5, 4
	v_writelane_b32 v254, s2, 5
	s_addc_u32 s1, s30, s1
	s_add_u32 s0, s0, s8
	v_writelane_b32 v254, s3, 6
	v_writelane_b32 v254, s29, 7
	v_writelane_b32 v254, s30, 8
	v_writelane_b32 v254, s8, 9
	s_addc_u32 s1, s1, s9
	s_add_u32 s2, s0, 0x40000
	v_writelane_b32 v254, s9, 10
	s_addc_u32 s3, s1, 0
	v_writelane_b32 v254, s2, 11
	s_nop 1
	v_writelane_b32 v254, s3, 12
	s_add_u32 s2, s0, 0x40080
	v_writelane_b32 v254, s0, 13
	s_addc_u32 s3, s1, 0
	s_nop 0
	v_writelane_b32 v254, s1, 14
	v_writelane_b32 v254, s2, 15
	s_nop 1
	v_writelane_b32 v254, s3, 16
	s_abs_i32 s3, s22
	v_cvt_f32_u32_e32 v0, s3
	s_sub_i32 s0, 0, s3
	v_rcp_iflag_f32_e32 v0, v0
	s_nop 0
	v_mul_f32_e32 v0, 0x4f7ffffe, v0
	v_cvt_u32_f32_e32 v0, v0
	s_nop 0
	v_readfirstlane_b32 s1, v0
	s_mul_i32 s0, s0, s1
	s_mul_hi_u32 s0, s1, s0
	s_add_i32 s1, s1, s0
	s_abs_i32 s0, s28
	v_writelane_b32 v254, s1, 17
	s_mul_hi_u32 s1, s0, s1
	s_mul_i32 s1, s1, s3
	s_sub_i32 s0, s0, s1
	s_ashr_i32 s1, s28, 31
	s_sub_i32 s2, s0, s3
	s_cmp_ge_u32 s0, s3
	s_cselect_b32 s0, s2, s0
	s_sub_i32 s2, s0, s3
	s_cmp_ge_u32 s0, s3
	s_cselect_b32 s0, s2, s0
	s_xor_b32 s0, s0, s1
	s_sub_i32 s1, s0, s1
	v_writelane_b32 v254, s28, 18
	s_cmp_lt_i32 s1, 32
	v_writelane_b32 v254, s3, 19
	s_cselect_b64 s[2:3], -1, 0
	v_writelane_b32 v254, s2, 20
	s_ashr_i32 s0, s1, 31
	v_mbcnt_lo_u32_b32 v0, -1, 0
	v_writelane_b32 v254, s3, 21
	v_writelane_b32 v254, s0, 22
	s_lshr_b32 s0, s0, 29
	s_add_i32 s0, s1, s0
	s_ashr_i32 s2, s0, 3
	s_and_b32 s0, s0, -8
	s_sub_i32 s0, s1, s0
	v_writelane_b32 v254, s2, 23
	s_cmp_gt_i32 s0, -1
	v_writelane_b32 v254, s1, 24
	s_cselect_b64 s[2:3], -1, 0
	v_writelane_b32 v254, s2, 25
	s_lshl_b32 s1, s0, 2
	s_mul_i32 s0, s0, 5
	v_writelane_b32 v254, s3, 26
	v_writelane_b32 v254, s1, 27
	v_writelane_b32 v254, s0, 28
	s_lshl_b32 s0, s27, 7
	s_lshl_b32 s1, s22, 7
	s_add_u32 s2, s42, 0x8bfd200
	v_writelane_b32 v254, s1, 29
	s_addc_u32 s3, s43, 0
	v_writelane_b32 v254, s2, 30
	v_mbcnt_hi_u32_b32 v197, -1, v0
	s_mov_b64 s[28:29], 0xc0080
	v_writelane_b32 v254, s3, 31
	v_writelane_b32 v254, s0, 32
	s_add_i32 s0, s0, 0xfffec000
	v_writelane_b32 v254, s0, 33
	s_lshl_b32 s0, s22, 6
	v_writelane_b32 v254, s0, 34
	s_add_u32 s0, s40, 0x3000
	v_writelane_b32 v254, s36, 35
	s_addc_u32 s1, s41, 0
	s_nop 0
	v_writelane_b32 v254, s37, 36
	v_writelane_b32 v254, s38, 37
	v_writelane_b32 v254, s39, 38
	v_writelane_b32 v254, s40, 39
	v_writelane_b32 v254, s41, 40
	v_writelane_b32 v254, s42, 41
	v_writelane_b32 v254, s43, 42
	v_writelane_b32 v254, s0, 43
	s_nop 1
	v_writelane_b32 v254, s1, 44
	s_mul_hi_i32 s0, s11, 0x160000
	v_writelane_b32 v254, s0, 45
	v_writelane_b32 v254, s11, 46
	s_mul_i32 s0, s11, 0x160000
	v_writelane_b32 v254, s0, 47
	s_add_i32 s0, 0, 0x22000
	v_writelane_b32 v254, s0, 48
	s_add_i32 s0, 0, 0x22004
	v_writelane_b32 v254, s0, 49
	s_add_i32 s0, 0, 0x22008
	v_writelane_b32 v254, s0, 50
	s_add_i32 s0, 0, 0xfffffe00
	v_writelane_b32 v254, s0, 51
	s_mov_b64 s[0:1], -1
	v_writelane_b32 v254, s0, 52
	s_nop 1
	v_writelane_b32 v254, s1, 53
	s_mov_b64 s[0:1], 0
	v_writelane_b32 v254, s0, 54
	s_nop 1
	v_writelane_b32 v254, s1, 55
	v_cmp_eq_u32_e64 s[0:1], 0, v192
	s_nop 1
	v_writelane_b32 v254, s0, 56
	s_nop 1
	v_writelane_b32 v254, s1, 57
	v_writelane_b32 v254, s66, 58
	s_mov_b32 s1, 0
	s_mov_b32 s30, s1
	v_writelane_b32 v254, s67, 59
	v_writelane_b32 v254, s27, 60
	v_writelane_b32 v254, s53, 61
	v_writelane_b32 v254, s60, 62
	s_nop 1
	v_writelane_b32 v254, s61, 63
	s_branch .LBB0_105
	s_nop 0
